# P1 QKV epilogue: rstd0 for next unit preloaded into v240-247, per-block load+vmcnt(0) removed (stores no longer drained per block)
# baseline (speedup 1.0000x reference)
.LBB0_138:
	s_add_u32 s18, s84, 0x1d00000
	s_mov_b64 s[28:29], 0x80
	s_addc_u32 s19, s85, 0
	s_add_i32 m0, s15, 0x18000
	v_lshl_add_u64 v[6:7], v[6:7], 0, s[28:29]
	s_bfe_u32 s35, s82, 0x20006
	s_waitcnt vmcnt(2)
	s_barrier
	global_load_lds_dwordx4 v[6:7], off
	v_lshl_add_u64 v[4:5], v[4:5], 0, s[28:29]
	s_add_i32 m0, s15, 0x1a000
	s_add_i32 s38, s15, 0x8000
	s_add_i32 s39, s15, 0xa000
	global_load_lds_dwordx4 v[4:5], off
	v_lshl_add_u64 v[0:1], v[0:1], 0, s[28:29]
	s_mov_b32 m0, s38
	s_add_u32 s20, s8, 0x40080
	global_load_lds_dwordx4 v[0:1], off
	v_lshl_add_u64 v[0:1], v[2:3], 0, s[28:29]
	s_mov_b32 m0, s39
	s_addc_u32 s21, s9, 0
	global_load_lds_dwordx4 v[0:1], off
	s_add_i32 m0, s15, 0x1c000
	v_lshl_add_u64 v[0:1], s[20:21], 0, v[130:131]
	global_load_lds_dwordx4 v[0:1], off
	v_lshl_add_u64 v[0:1], s[20:21], 0, v[134:135]
	s_add_i32 m0, s15, 0x1e000
	v_lshlrev_b32_e32 v3, 2, v8
	global_load_lds_dwordx4 v[0:1], off
	v_and_b32_e32 v0, 15, v8
	v_ashrrev_i32_e32 v1, 1, v8
	v_and_b32_e32 v138, -8, v1
	v_and_b32_e32 v1, 0xfffffc00, v13
	v_lshlrev_b32_e32 v140, 6, v0
	v_lshl_or_b32 v141, s2, 6, v0
	v_lshl_add_u32 v2, s2, 13, v1
	v_and_or_b32 v0, v8, 48, v140
	v_and_b32_e32 v3, 32, v3
	v_lshl_add_u32 v1, s35, 12, v1
	v_ashrrev_i32_e32 v139, 31, v138
	v_bitop3_b32 v2, v0, v2, v3 bitop3:0xde
	v_bitop3_b32 v180, v0, v1, v3 bitop3:0xde
	v_lshl_add_u64 v[0:1], v[138:139], 2, s[84:85]
	s_mov_b64 s[2:3], 0x1cc0000
	v_lshl_add_u64 v[142:143], v[0:1], 0, s[2:3]
	v_lshlrev_b32_e32 v0, 14, v9
	v_and_b32_e32 v0, 0xffff8000, v0
	v_lshl_add_u32 v0, v10, 11, v0
	v_and_b32_e32 v1, 1, v9
	v_lshl_or_b32 v0, v1, 6, v0
	v_lshl_add_u32 v144, v11, 1, v0
	v_lshlrev_b32_e32 v0, 14, v12
	s_cmpk_lt_u32 s82, 0x100
	v_and_b32_e32 v0, 0xffff8000, v0
	s_cselect_b64 s[30:31], -1, 0
	s_ashr_i32 s52, s67, 31
	s_ashr_i32 s53, s59, 31
	v_lshl_add_u32 v0, v14, 11, v0
	v_and_b32_e32 v1, 1, v12
	s_waitcnt vmcnt(6)
	s_add_u32 s54, s84, 0x14d00000
	v_lshl_or_b32 v0, v1, 6, v0
	s_addc_u32 s55, s85, 0
	v_lshl_add_u32 v146, v15, 1, v0
	s_add_i32 s57, 0, 0x10000
	s_add_i32 s58, 0, 0x14000
	v_mbcnt_lo_u32_b32 v0, -1, 0
	v_or_b32_e32 v181, 16, v141
	v_or_b32_e32 v182, 32, v141
	v_or_b32_e32 v183, 48, v141
	v_add_u32_e32 v184, 0x80, v141
	v_add_u32_e32 v185, 0x90, v141
	v_add_u32_e32 v186, 0xa0, v141
	v_add_u32_e32 v187, 0xb0, v141
	s_mov_b32 s80, s59
	v_mov_b32_e32 v145, v137
	v_mov_b32_e32 v147, v137
	v_mov_b64_e32 v[148:149], 0xc30
	v_mov_b64_e32 v[150:151], 0xc2f
	s_movk_i32 s56, 0x187
	v_add_u32_e32 v188, s57, v180
	v_add_u32_e32 v189, s58, v180
	v_add_u32_e32 v190, 0, v2
	v_mov_b32_e32 v191, 0x358637bd
	s_mov_b32 s59, 0x800000
	s_mov_b32 s60, 0x2ce00000
	s_mov_b32 s61, 0x2cf00000
	s_mov_b32 s62, 0x9180000
	s_mov_b32 s63, 0x2d100000
	s_mov_b32 s64, 0x9280000
	s_mov_b32 s65, 0x4100000
	s_mov_b32 s66, 0x5100000
	s_movk_i32 s81, 0x5ff
	s_mov_b64 s[40:41], 0x800
	v_mov_b32_e32 v192, 0x3e38aa3b
	v_mbcnt_hi_u32_b32 v193, -1, v0
	s_mov_b32 s68, 0
	s_barrier
	s_lshl_b32 s20, s14, 8
	v_add_u32_e32 v248, s20, v141
	v_mov_b32_e32 v249, 0
	v_lshl_add_u64 v[248:249], v[248:249], 2, s[18:19]
	global_load_dword v240, v[248:249], off
	global_load_dword v241, v[248:249], off offset:64
	global_load_dword v242, v[248:249], off offset:128
	global_load_dword v243, v[248:249], off offset:192
	global_load_dword v244, v[248:249], off offset:512
	global_load_dword v245, v[248:249], off offset:576
	global_load_dword v246, v[248:249], off offset:640
	global_load_dword v247, v[248:249], off offset:704
	s_waitcnt vmcnt(0)
	s_branch .LBB0_141

.LBB0_149:
	s_lshl_b32 s43, s14, 8
	v_add_u32_e32 v168, s43, v141
	v_ashrrev_i32_e32 v169, 31, v168
	v_lshl_add_u64 v[170:171], v[168:169], 2, s[18:19]
	v_mov_b32_e32 v136, v240
	v_cndmask_b32_e64 v169, 0, 1, s[50:51]
	v_cmp_ne_u32_e64 s[4:5], 1, v169
	s_andn2_b64 vcc, exec, s[50:51]
	v_pk_mul_f32 v[126:127], v[126:127], v[136:137] op_sel_hi:[1,0]
	v_pk_mul_f32 v[124:125], v[124:125], v[136:137] op_sel_hi:[1,0]
	v_pk_mul_f32 v[122:123], v[122:123], v[136:137] op_sel_hi:[1,0]
	v_pk_mul_f32 v[120:121], v[120:121], v[136:137] op_sel_hi:[1,0]
	v_pk_mul_f32 v[118:119], v[118:119], v[136:137] op_sel_hi:[1,0]
	v_pk_mul_f32 v[116:117], v[116:117], v[136:137] op_sel_hi:[1,0]
	v_pk_mul_f32 v[114:115], v[114:115], v[136:137] op_sel_hi:[1,0]
	v_pk_mul_f32 v[112:113], v[112:113], v[136:137] op_sel_hi:[1,0]
	s_cbranch_vccnz .LBB0_151
	v_pk_mul_f32 v[170:171], v[126:127], v[126:127]
	v_pk_mul_f32 v[172:173], v[124:125], v[124:125]
	v_mul_f32_e32 v136, v116, v116
	v_pk_mov_b32 v[174:175], v[172:173], v[170:171] op_sel:[1,0]
	v_mov_b32_e32 v173, v171
	v_pk_add_f32 v[170:171], v[174:175], v[172:173]
	v_pk_mul_f32 v[172:173], v[122:123], v[122:123]
	v_pk_mul_f32 v[174:175], v[120:121], v[120:121]
	v_pk_add_f32 v[170:171], v[170:171], v[170:171] op_sel_hi:[0,1]
	v_pk_mov_b32 v[176:177], v[174:175], v[172:173] op_sel:[1,0]
	v_mov_b32_e32 v175, v173
	v_pk_add_f32 v[172:173], v[176:177], v[174:175]
	v_pk_fma_f32 v[174:175], v[116:117], v[116:117], v[136:137] op_sel_hi:[1,1,0]
	v_mul_f32_e32 v136, v118, v118
	v_pk_add_f32 v[172:173], v[172:173], v[172:173] op_sel_hi:[0,1]
	v_pk_fma_f32 v[176:177], v[118:119], v[118:119], v[136:137] op_sel_hi:[1,1,0]
	v_mul_f32_e32 v174, v112, v112
	v_mul_f32_e32 v176, v113, v113
	v_mul_f32_e32 v170, v114, v114
	v_mul_f32_e32 v172, v115, v115
	v_pk_add_f32 v[174:175], v[174:175], v[176:177]
	v_pk_add_f32 v[170:171], v[170:171], v[172:173]
	v_xor_b32_e32 v169, 16, v193
	v_pk_add_f32 v[170:171], v[174:175], v[170:171]
	s_nop 0
	v_add_f32_e32 v136, v170, v171
	v_and_b32_e32 v170, 64, v193
	v_add_u32_e32 v170, 64, v170
	v_cmp_lt_i32_e32 vcc, v169, v170
	s_nop 1
	v_cndmask_b32_e32 v169, v193, v169, vcc
	v_lshlrev_b32_e32 v169, 2, v169
	ds_bpermute_b32 v169, v169, v136
	s_waitcnt lgkmcnt(0)
	v_add_f32_e32 v136, v136, v169
	v_xor_b32_e32 v169, 32, v193
	v_cmp_lt_i32_e32 vcc, v169, v170
	s_nop 1
	v_cndmask_b32_e32 v169, v193, v169, vcc
	v_lshlrev_b32_e32 v169, 2, v169
	ds_bpermute_b32 v169, v169, v136
	s_waitcnt lgkmcnt(0)
	v_add_f32_e32 v136, v136, v169
	v_fmamk_f32 v136, v136, 0x3c800000, v191
	v_mul_f32_e32 v169, 0x4b800000, v136
	v_cmp_gt_f32_e32 vcc, s59, v136
	s_nop 1
	v_cndmask_b32_e32 v136, v136, v169, vcc
	v_rsq_f32_e32 v136, v136
	s_nop 0
	v_mul_f32_e32 v169, 0x45800000, v136
	v_cndmask_b32_e32 v136, v136, v169, vcc
	v_pk_mul_f32 v[124:125], v[124:125], v[136:137] op_sel_hi:[1,0]
	v_pk_mul_f32 v[126:127], v[126:127], v[136:137] op_sel_hi:[1,0]
	v_pk_mul_f32 v[120:121], v[120:121], v[136:137] op_sel_hi:[1,0]
	v_pk_mul_f32 v[122:123], v[122:123], v[136:137] op_sel_hi:[1,0]
	v_pk_mul_f32 v[116:117], v[116:117], v[136:137] op_sel_hi:[1,0]
	v_pk_mul_f32 v[118:119], v[118:119], v[136:137] op_sel_hi:[1,0]
	v_pk_mul_f32 v[112:113], v[112:113], v[136:137] op_sel_hi:[1,0]
	v_pk_mul_f32 v[114:115], v[114:115], v[136:137] op_sel_hi:[1,0]
	v_pk_mul_f32 v[126:127], v[166:167], v[126:127]
	v_pk_mul_f32 v[124:125], v[164:165], v[124:125]
	v_pk_mul_f32 v[122:123], v[162:163], v[122:123]
	v_pk_mul_f32 v[120:121], v[160:161], v[120:121]
	v_pk_mul_f32 v[118:119], v[158:159], v[118:119]
	v_pk_mul_f32 v[116:117], v[156:157], v[116:117]
	v_pk_mul_f32 v[114:115], v[154:155], v[114:115]
	v_pk_mul_f32 v[112:113], v[152:153], v[112:113]

.LBB0_175:
	s_or_b64 exec, exec, s[8:9]
	s_nop 0
	v_mov_b32_e32 v112, v241
	s_and_b64 vcc, exec, s[4:5]
	v_pk_mul_f32 v[110:111], v[110:111], v[112:113] op_sel_hi:[1,0]
	v_pk_mul_f32 v[108:109], v[108:109], v[112:113] op_sel_hi:[1,0]
	v_pk_mul_f32 v[106:107], v[106:107], v[112:113] op_sel_hi:[1,0]
	v_pk_mul_f32 v[104:105], v[104:105], v[112:113] op_sel_hi:[1,0]
	v_pk_mul_f32 v[102:103], v[102:103], v[112:113] op_sel_hi:[1,0]
	v_pk_mul_f32 v[100:101], v[100:101], v[112:113] op_sel_hi:[1,0]
	v_pk_mul_f32 v[98:99], v[98:99], v[112:113] op_sel_hi:[1,0]
	v_pk_mul_f32 v[96:97], v[96:97], v[112:113] op_sel_hi:[1,0]
	s_cbranch_vccnz .LBB0_177
	v_pk_mul_f32 v[112:113], v[110:111], v[110:111]
	v_pk_mul_f32 v[114:115], v[108:109], v[108:109]
	s_nop 0
	v_pk_mov_b32 v[116:117], v[114:115], v[112:113] op_sel:[1,0]
	v_mov_b32_e32 v115, v113
	v_pk_add_f32 v[112:113], v[116:117], v[114:115]
	v_pk_mul_f32 v[114:115], v[106:107], v[106:107]
	v_pk_add_f32 v[112:113], v[112:113], v[112:113] op_sel_hi:[0,1]
	v_pk_mul_f32 v[116:117], v[104:105], v[104:105]
	v_mul_f32_e32 v112, v100, v100
	v_pk_mov_b32 v[118:119], v[116:117], v[114:115] op_sel:[1,0]
	v_mov_b32_e32 v117, v115
	v_pk_add_f32 v[114:115], v[118:119], v[116:117]
	v_pk_fma_f32 v[116:117], v[100:101], v[100:101], v[112:113] op_sel_hi:[1,1,0]
	v_mul_f32_e32 v112, v102, v102
	v_pk_add_f32 v[114:115], v[114:115], v[114:115] op_sel_hi:[0,1]
	v_pk_fma_f32 v[118:119], v[102:103], v[102:103], v[112:113] op_sel_hi:[1,1,0]
	v_mul_f32_e32 v116, v96, v96
	v_mul_f32_e32 v118, v97, v97
	v_mul_f32_e32 v112, v98, v98
	v_mul_f32_e32 v114, v99, v99
	v_pk_add_f32 v[116:117], v[116:117], v[118:119]
	v_pk_add_f32 v[112:113], v[112:113], v[114:115]
	v_and_b32_e32 v114, 64, v193
	v_pk_add_f32 v[112:113], v[116:117], v[112:113]
	v_add_u32_e32 v114, 64, v114
	v_add_f32_e32 v112, v112, v113
	v_xor_b32_e32 v113, 16, v193
	v_cmp_lt_i32_e32 vcc, v113, v114
	s_nop 1
	v_cndmask_b32_e32 v113, v193, v113, vcc
	v_lshlrev_b32_e32 v113, 2, v113
	ds_bpermute_b32 v113, v113, v112
	s_waitcnt lgkmcnt(0)
	v_add_f32_e32 v112, v112, v113
	v_xor_b32_e32 v113, 32, v193
	v_cmp_lt_i32_e32 vcc, v113, v114
	s_nop 1
	v_cndmask_b32_e32 v113, v193, v113, vcc
	v_lshlrev_b32_e32 v113, 2, v113
	ds_bpermute_b32 v113, v113, v112
	s_waitcnt lgkmcnt(0)
	v_add_f32_e32 v112, v112, v113
	v_fmamk_f32 v112, v112, 0x3c800000, v191
	v_mul_f32_e32 v113, 0x4b800000, v112
	v_cmp_gt_f32_e32 vcc, s59, v112
	s_nop 1
	v_cndmask_b32_e32 v112, v112, v113, vcc
	v_rsq_f32_e32 v112, v112
	s_nop 0
	v_mul_f32_e32 v113, 0x45800000, v112
	v_cndmask_b32_e32 v112, v112, v113, vcc
	v_pk_mul_f32 v[108:109], v[108:109], v[112:113] op_sel_hi:[1,0]
	v_pk_mul_f32 v[110:111], v[110:111], v[112:113] op_sel_hi:[1,0]
	v_pk_mul_f32 v[104:105], v[104:105], v[112:113] op_sel_hi:[1,0]
	v_pk_mul_f32 v[106:107], v[106:107], v[112:113] op_sel_hi:[1,0]
	v_pk_mul_f32 v[100:101], v[100:101], v[112:113] op_sel_hi:[1,0]
	v_pk_mul_f32 v[102:103], v[102:103], v[112:113] op_sel_hi:[1,0]
	v_pk_mul_f32 v[96:97], v[96:97], v[112:113] op_sel_hi:[1,0]
	v_pk_mul_f32 v[98:99], v[98:99], v[112:113] op_sel_hi:[1,0]
	v_pk_mul_f32 v[110:111], v[166:167], v[110:111]
	v_pk_mul_f32 v[108:109], v[164:165], v[108:109]
	v_pk_mul_f32 v[106:107], v[162:163], v[106:107]
	v_pk_mul_f32 v[104:105], v[160:161], v[104:105]
	v_pk_mul_f32 v[102:103], v[158:159], v[102:103]
	v_pk_mul_f32 v[100:101], v[156:157], v[100:101]
	v_pk_mul_f32 v[98:99], v[154:155], v[98:99]
	v_pk_mul_f32 v[96:97], v[152:153], v[96:97]

.LBB0_201:
	s_or_b64 exec, exec, s[20:21]
	s_nop 0
	v_mov_b32_e32 v96, v242
	s_and_b64 vcc, exec, s[4:5]
	v_pk_mul_f32 v[94:95], v[94:95], v[96:97] op_sel_hi:[1,0]
	v_pk_mul_f32 v[92:93], v[92:93], v[96:97] op_sel_hi:[1,0]
	v_pk_mul_f32 v[90:91], v[90:91], v[96:97] op_sel_hi:[1,0]
	v_pk_mul_f32 v[88:89], v[88:89], v[96:97] op_sel_hi:[1,0]
	v_pk_mul_f32 v[86:87], v[86:87], v[96:97] op_sel_hi:[1,0]
	v_pk_mul_f32 v[84:85], v[84:85], v[96:97] op_sel_hi:[1,0]
	v_pk_mul_f32 v[82:83], v[82:83], v[96:97] op_sel_hi:[1,0]
	v_pk_mul_f32 v[80:81], v[80:81], v[96:97] op_sel_hi:[1,0]
	s_cbranch_vccnz .LBB0_203
	v_pk_mul_f32 v[96:97], v[94:95], v[94:95]
	v_pk_mul_f32 v[98:99], v[92:93], v[92:93]
	s_nop 0
	v_pk_mov_b32 v[100:101], v[98:99], v[96:97] op_sel:[1,0]
	v_mov_b32_e32 v99, v97
	v_pk_add_f32 v[96:97], v[100:101], v[98:99]
	v_pk_mul_f32 v[98:99], v[90:91], v[90:91]
	v_pk_add_f32 v[96:97], v[96:97], v[96:97] op_sel_hi:[0,1]
	v_pk_mul_f32 v[100:101], v[88:89], v[88:89]
	v_mul_f32_e32 v96, v84, v84
	v_pk_mov_b32 v[102:103], v[100:101], v[98:99] op_sel:[1,0]
	v_mov_b32_e32 v101, v99
	v_pk_add_f32 v[98:99], v[102:103], v[100:101]
	v_pk_fma_f32 v[100:101], v[84:85], v[84:85], v[96:97] op_sel_hi:[1,1,0]
	v_mul_f32_e32 v96, v86, v86
	v_pk_add_f32 v[98:99], v[98:99], v[98:99] op_sel_hi:[0,1]
	v_pk_fma_f32 v[102:103], v[86:87], v[86:87], v[96:97] op_sel_hi:[1,1,0]
	v_mul_f32_e32 v100, v80, v80
	v_mul_f32_e32 v102, v81, v81
	v_mul_f32_e32 v96, v82, v82
	v_mul_f32_e32 v98, v83, v83
	v_pk_add_f32 v[100:101], v[100:101], v[102:103]
	v_pk_add_f32 v[96:97], v[96:97], v[98:99]
	v_and_b32_e32 v98, 64, v193
	v_pk_add_f32 v[96:97], v[100:101], v[96:97]
	v_add_u32_e32 v98, 64, v98
	v_add_f32_e32 v96, v96, v97
	v_xor_b32_e32 v97, 16, v193
	v_cmp_lt_i32_e32 vcc, v97, v98
	s_nop 1
	v_cndmask_b32_e32 v97, v193, v97, vcc
	v_lshlrev_b32_e32 v97, 2, v97
	ds_bpermute_b32 v97, v97, v96
	s_waitcnt lgkmcnt(0)
	v_add_f32_e32 v96, v96, v97
	v_xor_b32_e32 v97, 32, v193
	v_cmp_lt_i32_e32 vcc, v97, v98
	s_nop 1
	v_cndmask_b32_e32 v97, v193, v97, vcc
	v_lshlrev_b32_e32 v97, 2, v97
	ds_bpermute_b32 v97, v97, v96
	s_waitcnt lgkmcnt(0)
	v_add_f32_e32 v96, v96, v97
	v_fmamk_f32 v96, v96, 0x3c800000, v191
	v_mul_f32_e32 v97, 0x4b800000, v96
	v_cmp_gt_f32_e32 vcc, s59, v96
	s_nop 1
	v_cndmask_b32_e32 v96, v96, v97, vcc
	v_rsq_f32_e32 v96, v96
	s_nop 0
	v_mul_f32_e32 v97, 0x45800000, v96
	v_cndmask_b32_e32 v96, v96, v97, vcc
	v_pk_mul_f32 v[92:93], v[92:93], v[96:97] op_sel_hi:[1,0]
	v_pk_mul_f32 v[94:95], v[94:95], v[96:97] op_sel_hi:[1,0]
	v_pk_mul_f32 v[88:89], v[88:89], v[96:97] op_sel_hi:[1,0]
	v_pk_mul_f32 v[90:91], v[90:91], v[96:97] op_sel_hi:[1,0]
	v_pk_mul_f32 v[84:85], v[84:85], v[96:97] op_sel_hi:[1,0]
	v_pk_mul_f32 v[86:87], v[86:87], v[96:97] op_sel_hi:[1,0]
	v_pk_mul_f32 v[80:81], v[80:81], v[96:97] op_sel_hi:[1,0]
	v_pk_mul_f32 v[82:83], v[82:83], v[96:97] op_sel_hi:[1,0]
	v_pk_mul_f32 v[94:95], v[166:167], v[94:95]
	v_pk_mul_f32 v[92:93], v[164:165], v[92:93]
	v_pk_mul_f32 v[90:91], v[162:163], v[90:91]
	v_pk_mul_f32 v[88:89], v[160:161], v[88:89]
	v_pk_mul_f32 v[86:87], v[158:159], v[86:87]
	v_pk_mul_f32 v[84:85], v[156:157], v[84:85]
	v_pk_mul_f32 v[82:83], v[154:155], v[82:83]
	v_pk_mul_f32 v[80:81], v[152:153], v[80:81]

.LBB0_227:
	s_or_b64 exec, exec, s[20:21]
	s_nop 0
	v_mov_b32_e32 v80, v243
	s_and_b64 vcc, exec, s[4:5]
	v_pk_mul_f32 v[78:79], v[78:79], v[80:81] op_sel_hi:[1,0]
	v_pk_mul_f32 v[76:77], v[76:77], v[80:81] op_sel_hi:[1,0]
	v_pk_mul_f32 v[74:75], v[74:75], v[80:81] op_sel_hi:[1,0]
	v_pk_mul_f32 v[72:73], v[72:73], v[80:81] op_sel_hi:[1,0]
	v_pk_mul_f32 v[70:71], v[70:71], v[80:81] op_sel_hi:[1,0]
	v_pk_mul_f32 v[68:69], v[68:69], v[80:81] op_sel_hi:[1,0]
	v_pk_mul_f32 v[66:67], v[66:67], v[80:81] op_sel_hi:[1,0]
	v_pk_mul_f32 v[64:65], v[64:65], v[80:81] op_sel_hi:[1,0]
	s_cbranch_vccnz .LBB0_229
	v_pk_mul_f32 v[80:81], v[78:79], v[78:79]
	v_pk_mul_f32 v[82:83], v[76:77], v[76:77]
	s_nop 0
	v_pk_mov_b32 v[84:85], v[82:83], v[80:81] op_sel:[1,0]
	v_mov_b32_e32 v83, v81
	v_pk_add_f32 v[80:81], v[84:85], v[82:83]
	v_pk_mul_f32 v[82:83], v[74:75], v[74:75]
	v_pk_add_f32 v[80:81], v[80:81], v[80:81] op_sel_hi:[0,1]
	v_pk_mul_f32 v[84:85], v[72:73], v[72:73]
	v_mul_f32_e32 v80, v68, v68
	v_pk_mov_b32 v[86:87], v[84:85], v[82:83] op_sel:[1,0]
	v_mov_b32_e32 v85, v83
	v_pk_add_f32 v[82:83], v[86:87], v[84:85]
	v_pk_fma_f32 v[84:85], v[68:69], v[68:69], v[80:81] op_sel_hi:[1,1,0]
	v_mul_f32_e32 v80, v70, v70
	v_pk_add_f32 v[82:83], v[82:83], v[82:83] op_sel_hi:[0,1]
	v_pk_fma_f32 v[86:87], v[70:71], v[70:71], v[80:81] op_sel_hi:[1,1,0]
	v_mul_f32_e32 v84, v64, v64
	v_mul_f32_e32 v86, v65, v65
	v_mul_f32_e32 v80, v66, v66
	v_mul_f32_e32 v82, v67, v67
	v_pk_add_f32 v[84:85], v[84:85], v[86:87]
	v_pk_add_f32 v[80:81], v[80:81], v[82:83]
	v_and_b32_e32 v82, 64, v193
	v_pk_add_f32 v[80:81], v[84:85], v[80:81]
	v_add_u32_e32 v82, 64, v82
	v_add_f32_e32 v80, v80, v81
	v_xor_b32_e32 v81, 16, v193
	v_cmp_lt_i32_e32 vcc, v81, v82
	s_nop 1
	v_cndmask_b32_e32 v81, v193, v81, vcc
	v_lshlrev_b32_e32 v81, 2, v81
	ds_bpermute_b32 v81, v81, v80
	s_waitcnt lgkmcnt(0)
	v_add_f32_e32 v80, v80, v81
	v_xor_b32_e32 v81, 32, v193
	v_cmp_lt_i32_e32 vcc, v81, v82
	s_nop 1
	v_cndmask_b32_e32 v81, v193, v81, vcc
	v_lshlrev_b32_e32 v81, 2, v81
	ds_bpermute_b32 v81, v81, v80
	s_waitcnt lgkmcnt(0)
	v_add_f32_e32 v80, v80, v81
	v_fmamk_f32 v80, v80, 0x3c800000, v191
	v_mul_f32_e32 v81, 0x4b800000, v80
	v_cmp_gt_f32_e32 vcc, s59, v80
	s_nop 1
	v_cndmask_b32_e32 v80, v80, v81, vcc
	v_rsq_f32_e32 v80, v80
	s_nop 0
	v_mul_f32_e32 v81, 0x45800000, v80
	v_cndmask_b32_e32 v80, v80, v81, vcc
	v_pk_mul_f32 v[76:77], v[76:77], v[80:81] op_sel_hi:[1,0]
	v_pk_mul_f32 v[78:79], v[78:79], v[80:81] op_sel_hi:[1,0]
	v_pk_mul_f32 v[72:73], v[72:73], v[80:81] op_sel_hi:[1,0]
	v_pk_mul_f32 v[74:75], v[74:75], v[80:81] op_sel_hi:[1,0]
	v_pk_mul_f32 v[68:69], v[68:69], v[80:81] op_sel_hi:[1,0]
	v_pk_mul_f32 v[70:71], v[70:71], v[80:81] op_sel_hi:[1,0]
	v_pk_mul_f32 v[64:65], v[64:65], v[80:81] op_sel_hi:[1,0]
	v_pk_mul_f32 v[66:67], v[66:67], v[80:81] op_sel_hi:[1,0]
	v_pk_mul_f32 v[78:79], v[166:167], v[78:79]
	v_pk_mul_f32 v[76:77], v[164:165], v[76:77]
	v_pk_mul_f32 v[74:75], v[162:163], v[74:75]
	v_pk_mul_f32 v[72:73], v[160:161], v[72:73]
	v_pk_mul_f32 v[70:71], v[158:159], v[70:71]
	v_pk_mul_f32 v[68:69], v[156:157], v[68:69]
	v_pk_mul_f32 v[66:67], v[154:155], v[66:67]
	v_pk_mul_f32 v[64:65], v[152:153], v[64:65]

.LBB0_253:
	s_or_b64 exec, exec, s[20:21]
	s_nop 0
	v_mov_b32_e32 v64, v244
	s_and_b64 vcc, exec, s[4:5]
	v_pk_mul_f32 v[62:63], v[62:63], v[64:65] op_sel_hi:[1,0]
	v_pk_mul_f32 v[60:61], v[60:61], v[64:65] op_sel_hi:[1,0]
	v_pk_mul_f32 v[58:59], v[58:59], v[64:65] op_sel_hi:[1,0]
	v_pk_mul_f32 v[56:57], v[56:57], v[64:65] op_sel_hi:[1,0]
	v_pk_mul_f32 v[54:55], v[54:55], v[64:65] op_sel_hi:[1,0]
	v_pk_mul_f32 v[52:53], v[52:53], v[64:65] op_sel_hi:[1,0]
	v_pk_mul_f32 v[50:51], v[50:51], v[64:65] op_sel_hi:[1,0]
	v_pk_mul_f32 v[48:49], v[48:49], v[64:65] op_sel_hi:[1,0]
	s_cbranch_vccnz .LBB0_255
	v_pk_mul_f32 v[64:65], v[62:63], v[62:63]
	v_pk_mul_f32 v[66:67], v[60:61], v[60:61]
	s_nop 0
	v_pk_mov_b32 v[68:69], v[66:67], v[64:65] op_sel:[1,0]
	v_mov_b32_e32 v67, v65
	v_pk_add_f32 v[64:65], v[68:69], v[66:67]
	v_pk_mul_f32 v[66:67], v[58:59], v[58:59]
	v_pk_add_f32 v[64:65], v[64:65], v[64:65] op_sel_hi:[0,1]
	v_pk_mul_f32 v[68:69], v[56:57], v[56:57]
	v_mul_f32_e32 v64, v52, v52
	v_pk_mov_b32 v[70:71], v[68:69], v[66:67] op_sel:[1,0]
	v_mov_b32_e32 v69, v67
	v_pk_add_f32 v[66:67], v[70:71], v[68:69]
	v_pk_fma_f32 v[68:69], v[52:53], v[52:53], v[64:65] op_sel_hi:[1,1,0]
	v_mul_f32_e32 v64, v54, v54
	v_pk_add_f32 v[66:67], v[66:67], v[66:67] op_sel_hi:[0,1]
	v_pk_fma_f32 v[70:71], v[54:55], v[54:55], v[64:65] op_sel_hi:[1,1,0]
	v_mul_f32_e32 v68, v48, v48
	v_mul_f32_e32 v70, v49, v49
	v_mul_f32_e32 v64, v50, v50
	v_mul_f32_e32 v66, v51, v51
	v_pk_add_f32 v[68:69], v[68:69], v[70:71]
	v_pk_add_f32 v[64:65], v[64:65], v[66:67]
	v_and_b32_e32 v66, 64, v193
	v_pk_add_f32 v[64:65], v[68:69], v[64:65]
	v_add_u32_e32 v66, 64, v66
	v_add_f32_e32 v64, v64, v65
	v_xor_b32_e32 v65, 16, v193
	v_cmp_lt_i32_e32 vcc, v65, v66
	s_nop 1
	v_cndmask_b32_e32 v65, v193, v65, vcc
	v_lshlrev_b32_e32 v65, 2, v65
	ds_bpermute_b32 v65, v65, v64
	s_waitcnt lgkmcnt(0)
	v_add_f32_e32 v64, v64, v65
	v_xor_b32_e32 v65, 32, v193
	v_cmp_lt_i32_e32 vcc, v65, v66
	s_nop 1
	v_cndmask_b32_e32 v65, v193, v65, vcc
	v_lshlrev_b32_e32 v65, 2, v65
	ds_bpermute_b32 v65, v65, v64
	s_waitcnt lgkmcnt(0)
	v_add_f32_e32 v64, v64, v65
	v_fmamk_f32 v64, v64, 0x3c800000, v191
	v_mul_f32_e32 v65, 0x4b800000, v64
	v_cmp_gt_f32_e32 vcc, s59, v64
	s_nop 1
	v_cndmask_b32_e32 v64, v64, v65, vcc
	v_rsq_f32_e32 v64, v64
	s_nop 0
	v_mul_f32_e32 v65, 0x45800000, v64
	v_cndmask_b32_e32 v64, v64, v65, vcc
	v_pk_mul_f32 v[60:61], v[60:61], v[64:65] op_sel_hi:[1,0]
	v_pk_mul_f32 v[62:63], v[62:63], v[64:65] op_sel_hi:[1,0]
	v_pk_mul_f32 v[56:57], v[56:57], v[64:65] op_sel_hi:[1,0]
	v_pk_mul_f32 v[58:59], v[58:59], v[64:65] op_sel_hi:[1,0]
	v_pk_mul_f32 v[52:53], v[52:53], v[64:65] op_sel_hi:[1,0]
	v_pk_mul_f32 v[54:55], v[54:55], v[64:65] op_sel_hi:[1,0]
	v_pk_mul_f32 v[48:49], v[48:49], v[64:65] op_sel_hi:[1,0]
	v_pk_mul_f32 v[50:51], v[50:51], v[64:65] op_sel_hi:[1,0]
	v_pk_mul_f32 v[62:63], v[166:167], v[62:63]
	v_pk_mul_f32 v[60:61], v[164:165], v[60:61]
	v_pk_mul_f32 v[58:59], v[162:163], v[58:59]
	v_pk_mul_f32 v[56:57], v[160:161], v[56:57]
	v_pk_mul_f32 v[54:55], v[158:159], v[54:55]
	v_pk_mul_f32 v[52:53], v[156:157], v[52:53]
	v_pk_mul_f32 v[50:51], v[154:155], v[50:51]
	v_pk_mul_f32 v[48:49], v[152:153], v[48:49]

.LBB0_279:
	s_or_b64 exec, exec, s[20:21]
	s_nop 0
	v_mov_b32_e32 v48, v245
	s_and_b64 vcc, exec, s[4:5]
	v_pk_mul_f32 v[46:47], v[46:47], v[48:49] op_sel_hi:[1,0]
	v_pk_mul_f32 v[44:45], v[44:45], v[48:49] op_sel_hi:[1,0]
	v_pk_mul_f32 v[42:43], v[42:43], v[48:49] op_sel_hi:[1,0]
	v_pk_mul_f32 v[40:41], v[40:41], v[48:49] op_sel_hi:[1,0]
	v_pk_mul_f32 v[38:39], v[38:39], v[48:49] op_sel_hi:[1,0]
	v_pk_mul_f32 v[36:37], v[36:37], v[48:49] op_sel_hi:[1,0]
	v_pk_mul_f32 v[34:35], v[34:35], v[48:49] op_sel_hi:[1,0]
	v_pk_mul_f32 v[32:33], v[32:33], v[48:49] op_sel_hi:[1,0]
	s_cbranch_vccnz .LBB0_281
	v_pk_mul_f32 v[48:49], v[46:47], v[46:47]
	v_pk_mul_f32 v[50:51], v[44:45], v[44:45]
	s_nop 0
	v_pk_mov_b32 v[52:53], v[50:51], v[48:49] op_sel:[1,0]
	v_mov_b32_e32 v51, v49
	v_pk_add_f32 v[48:49], v[52:53], v[50:51]
	v_pk_mul_f32 v[50:51], v[42:43], v[42:43]
	v_pk_add_f32 v[48:49], v[48:49], v[48:49] op_sel_hi:[0,1]
	v_pk_mul_f32 v[52:53], v[40:41], v[40:41]
	v_mul_f32_e32 v48, v36, v36
	v_pk_mov_b32 v[54:55], v[52:53], v[50:51] op_sel:[1,0]
	v_mov_b32_e32 v53, v51
	v_pk_add_f32 v[50:51], v[54:55], v[52:53]
	v_pk_fma_f32 v[52:53], v[36:37], v[36:37], v[48:49] op_sel_hi:[1,1,0]
	v_mul_f32_e32 v48, v38, v38
	v_pk_add_f32 v[50:51], v[50:51], v[50:51] op_sel_hi:[0,1]
	v_pk_fma_f32 v[54:55], v[38:39], v[38:39], v[48:49] op_sel_hi:[1,1,0]
	v_mul_f32_e32 v52, v32, v32
	v_mul_f32_e32 v54, v33, v33
	v_mul_f32_e32 v48, v34, v34
	v_mul_f32_e32 v50, v35, v35
	v_pk_add_f32 v[52:53], v[52:53], v[54:55]
	v_pk_add_f32 v[48:49], v[48:49], v[50:51]
	v_and_b32_e32 v50, 64, v193
	v_pk_add_f32 v[48:49], v[52:53], v[48:49]
	v_add_u32_e32 v50, 64, v50
	v_add_f32_e32 v48, v48, v49
	v_xor_b32_e32 v49, 16, v193
	v_cmp_lt_i32_e32 vcc, v49, v50
	s_nop 1
	v_cndmask_b32_e32 v49, v193, v49, vcc
	v_lshlrev_b32_e32 v49, 2, v49
	ds_bpermute_b32 v49, v49, v48
	s_waitcnt lgkmcnt(0)
	v_add_f32_e32 v48, v48, v49
	v_xor_b32_e32 v49, 32, v193
	v_cmp_lt_i32_e32 vcc, v49, v50
	s_nop 1
	v_cndmask_b32_e32 v49, v193, v49, vcc
	v_lshlrev_b32_e32 v49, 2, v49
	ds_bpermute_b32 v49, v49, v48
	s_waitcnt lgkmcnt(0)
	v_add_f32_e32 v48, v48, v49
	v_fmamk_f32 v48, v48, 0x3c800000, v191
	v_mul_f32_e32 v49, 0x4b800000, v48
	v_cmp_gt_f32_e32 vcc, s59, v48
	s_nop 1
	v_cndmask_b32_e32 v48, v48, v49, vcc
	v_rsq_f32_e32 v48, v48
	s_nop 0
	v_mul_f32_e32 v49, 0x45800000, v48
	v_cndmask_b32_e32 v48, v48, v49, vcc
	v_pk_mul_f32 v[44:45], v[44:45], v[48:49] op_sel_hi:[1,0]
	v_pk_mul_f32 v[46:47], v[46:47], v[48:49] op_sel_hi:[1,0]
	v_pk_mul_f32 v[40:41], v[40:41], v[48:49] op_sel_hi:[1,0]
	v_pk_mul_f32 v[42:43], v[42:43], v[48:49] op_sel_hi:[1,0]
	v_pk_mul_f32 v[36:37], v[36:37], v[48:49] op_sel_hi:[1,0]
	v_pk_mul_f32 v[38:39], v[38:39], v[48:49] op_sel_hi:[1,0]
	v_pk_mul_f32 v[32:33], v[32:33], v[48:49] op_sel_hi:[1,0]
	v_pk_mul_f32 v[34:35], v[34:35], v[48:49] op_sel_hi:[1,0]
	v_pk_mul_f32 v[46:47], v[166:167], v[46:47]
	v_pk_mul_f32 v[44:45], v[164:165], v[44:45]
	v_pk_mul_f32 v[42:43], v[162:163], v[42:43]
	v_pk_mul_f32 v[40:41], v[160:161], v[40:41]
	v_pk_mul_f32 v[38:39], v[158:159], v[38:39]
	v_pk_mul_f32 v[36:37], v[156:157], v[36:37]
	v_pk_mul_f32 v[34:35], v[154:155], v[34:35]
	v_pk_mul_f32 v[32:33], v[152:153], v[32:33]

.LBB0_305:
	s_or_b64 exec, exec, s[20:21]
	s_nop 0
	v_mov_b32_e32 v32, v246
	s_and_b64 vcc, exec, s[4:5]
	v_pk_mul_f32 v[30:31], v[30:31], v[32:33] op_sel_hi:[1,0]
	v_pk_mul_f32 v[28:29], v[28:29], v[32:33] op_sel_hi:[1,0]
	v_pk_mul_f32 v[26:27], v[26:27], v[32:33] op_sel_hi:[1,0]
	v_pk_mul_f32 v[24:25], v[24:25], v[32:33] op_sel_hi:[1,0]
	v_pk_mul_f32 v[22:23], v[22:23], v[32:33] op_sel_hi:[1,0]
	v_pk_mul_f32 v[20:21], v[20:21], v[32:33] op_sel_hi:[1,0]
	v_pk_mul_f32 v[18:19], v[18:19], v[32:33] op_sel_hi:[1,0]
	v_pk_mul_f32 v[16:17], v[16:17], v[32:33] op_sel_hi:[1,0]
	s_cbranch_vccnz .LBB0_307
	v_pk_mul_f32 v[32:33], v[30:31], v[30:31]
	v_pk_mul_f32 v[34:35], v[28:29], v[28:29]
	s_nop 0
	v_pk_mov_b32 v[36:37], v[34:35], v[32:33] op_sel:[1,0]
	v_mov_b32_e32 v35, v33
	v_pk_add_f32 v[32:33], v[36:37], v[34:35]
	v_pk_mul_f32 v[34:35], v[26:27], v[26:27]
	v_pk_add_f32 v[32:33], v[32:33], v[32:33] op_sel_hi:[0,1]
	v_pk_mul_f32 v[36:37], v[24:25], v[24:25]
	v_mul_f32_e32 v32, v20, v20
	v_pk_mov_b32 v[38:39], v[36:37], v[34:35] op_sel:[1,0]
	v_mov_b32_e32 v37, v35
	v_pk_add_f32 v[34:35], v[38:39], v[36:37]
	v_pk_fma_f32 v[36:37], v[20:21], v[20:21], v[32:33] op_sel_hi:[1,1,0]
	v_mul_f32_e32 v32, v22, v22
	v_pk_add_f32 v[34:35], v[34:35], v[34:35] op_sel_hi:[0,1]
	v_pk_fma_f32 v[38:39], v[22:23], v[22:23], v[32:33] op_sel_hi:[1,1,0]
	v_mul_f32_e32 v36, v16, v16
	v_mul_f32_e32 v38, v17, v17
	v_mul_f32_e32 v32, v18, v18
	v_mul_f32_e32 v34, v19, v19
	v_pk_add_f32 v[36:37], v[36:37], v[38:39]
	v_pk_add_f32 v[32:33], v[32:33], v[34:35]
	v_and_b32_e32 v34, 64, v193
	v_pk_add_f32 v[32:33], v[36:37], v[32:33]
	v_add_u32_e32 v34, 64, v34
	v_add_f32_e32 v32, v32, v33
	v_xor_b32_e32 v33, 16, v193
	v_cmp_lt_i32_e32 vcc, v33, v34
	s_nop 1
	v_cndmask_b32_e32 v33, v193, v33, vcc
	v_lshlrev_b32_e32 v33, 2, v33
	ds_bpermute_b32 v33, v33, v32
	s_waitcnt lgkmcnt(0)
	v_add_f32_e32 v32, v32, v33
	v_xor_b32_e32 v33, 32, v193
	v_cmp_lt_i32_e32 vcc, v33, v34
	s_nop 1
	v_cndmask_b32_e32 v33, v193, v33, vcc
	v_lshlrev_b32_e32 v33, 2, v33
	ds_bpermute_b32 v33, v33, v32
	s_waitcnt lgkmcnt(0)
	v_add_f32_e32 v32, v32, v33
	v_fmamk_f32 v32, v32, 0x3c800000, v191
	v_mul_f32_e32 v33, 0x4b800000, v32
	v_cmp_gt_f32_e32 vcc, s59, v32
	s_nop 1
	v_cndmask_b32_e32 v32, v32, v33, vcc
	v_rsq_f32_e32 v32, v32
	s_nop 0
	v_mul_f32_e32 v33, 0x45800000, v32
	v_cndmask_b32_e32 v32, v32, v33, vcc
	v_pk_mul_f32 v[28:29], v[28:29], v[32:33] op_sel_hi:[1,0]
	v_pk_mul_f32 v[30:31], v[30:31], v[32:33] op_sel_hi:[1,0]
	v_pk_mul_f32 v[24:25], v[24:25], v[32:33] op_sel_hi:[1,0]
	v_pk_mul_f32 v[26:27], v[26:27], v[32:33] op_sel_hi:[1,0]
	v_pk_mul_f32 v[20:21], v[20:21], v[32:33] op_sel_hi:[1,0]
	v_pk_mul_f32 v[22:23], v[22:23], v[32:33] op_sel_hi:[1,0]
	v_pk_mul_f32 v[16:17], v[16:17], v[32:33] op_sel_hi:[1,0]
	v_pk_mul_f32 v[18:19], v[18:19], v[32:33] op_sel_hi:[1,0]
	v_pk_mul_f32 v[30:31], v[166:167], v[30:31]
	v_pk_mul_f32 v[28:29], v[164:165], v[28:29]
	v_pk_mul_f32 v[26:27], v[162:163], v[26:27]
	v_pk_mul_f32 v[24:25], v[160:161], v[24:25]
	v_pk_mul_f32 v[22:23], v[158:159], v[22:23]
	v_pk_mul_f32 v[20:21], v[156:157], v[20:21]
	v_pk_mul_f32 v[18:19], v[154:155], v[18:19]
	v_pk_mul_f32 v[16:17], v[152:153], v[16:17]

.LBB0_331:
	s_or_b64 exec, exec, s[20:21]
	s_nop 0
	v_mov_b32_e32 v16, v247
	s_and_b64 vcc, exec, s[4:5]
	v_pk_mul_f32 v[14:15], v[14:15], v[16:17] op_sel_hi:[1,0]
	v_pk_mul_f32 v[12:13], v[12:13], v[16:17] op_sel_hi:[1,0]
	v_pk_mul_f32 v[10:11], v[10:11], v[16:17] op_sel_hi:[1,0]
	v_pk_mul_f32 v[8:9], v[8:9], v[16:17] op_sel_hi:[1,0]
	v_pk_mul_f32 v[6:7], v[6:7], v[16:17] op_sel_hi:[1,0]
	v_pk_mul_f32 v[4:5], v[4:5], v[16:17] op_sel_hi:[1,0]
	v_pk_mul_f32 v[2:3], v[2:3], v[16:17] op_sel_hi:[1,0]
	v_pk_mul_f32 v[0:1], v[0:1], v[16:17] op_sel_hi:[1,0]
	s_cbranch_vccnz .LBB0_333
	v_pk_mul_f32 v[16:17], v[14:15], v[14:15]
	v_pk_mul_f32 v[18:19], v[12:13], v[12:13]
	s_nop 0
	v_pk_mov_b32 v[20:21], v[18:19], v[16:17] op_sel:[1,0]
	v_mov_b32_e32 v19, v17
	v_pk_add_f32 v[16:17], v[20:21], v[18:19]
	v_pk_mul_f32 v[18:19], v[10:11], v[10:11]
	v_pk_add_f32 v[16:17], v[16:17], v[16:17] op_sel_hi:[0,1]
	v_pk_mul_f32 v[20:21], v[8:9], v[8:9]
	v_mul_f32_e32 v16, v4, v4
	v_pk_mov_b32 v[22:23], v[20:21], v[18:19] op_sel:[1,0]
	v_mov_b32_e32 v21, v19
	v_pk_add_f32 v[18:19], v[22:23], v[20:21]
	v_pk_fma_f32 v[20:21], v[4:5], v[4:5], v[16:17] op_sel_hi:[1,1,0]
	v_mul_f32_e32 v16, v6, v6
	v_pk_add_f32 v[18:19], v[18:19], v[18:19] op_sel_hi:[0,1]
	v_pk_fma_f32 v[22:23], v[6:7], v[6:7], v[16:17] op_sel_hi:[1,1,0]
	v_mul_f32_e32 v20, v0, v0
	v_mul_f32_e32 v22, v1, v1
	v_mul_f32_e32 v16, v2, v2
	v_mul_f32_e32 v18, v3, v3
	v_pk_add_f32 v[20:21], v[20:21], v[22:23]
	v_pk_add_f32 v[16:17], v[16:17], v[18:19]
	v_and_b32_e32 v18, 64, v193
	v_pk_add_f32 v[16:17], v[20:21], v[16:17]
	v_add_u32_e32 v18, 64, v18
	v_add_f32_e32 v16, v16, v17
	v_xor_b32_e32 v17, 16, v193
	v_cmp_lt_i32_e32 vcc, v17, v18
	s_nop 1
	v_cndmask_b32_e32 v17, v193, v17, vcc
	v_lshlrev_b32_e32 v17, 2, v17
	ds_bpermute_b32 v17, v17, v16
	s_waitcnt lgkmcnt(0)
	v_add_f32_e32 v16, v16, v17
	v_xor_b32_e32 v17, 32, v193
	v_cmp_lt_i32_e32 vcc, v17, v18
	s_nop 1
	v_cndmask_b32_e32 v17, v193, v17, vcc
	v_lshlrev_b32_e32 v17, 2, v17
	ds_bpermute_b32 v17, v17, v16
	s_waitcnt lgkmcnt(0)
	v_add_f32_e32 v16, v16, v17
	v_fmamk_f32 v16, v16, 0x3c800000, v191
	v_mul_f32_e32 v17, 0x4b800000, v16
	v_cmp_gt_f32_e32 vcc, s59, v16
	s_nop 1
	v_cndmask_b32_e32 v16, v16, v17, vcc
	v_rsq_f32_e32 v16, v16
	s_nop 0
	v_mul_f32_e32 v17, 0x45800000, v16
	v_cndmask_b32_e32 v16, v16, v17, vcc
	v_pk_mul_f32 v[12:13], v[12:13], v[16:17] op_sel_hi:[1,0]
	v_pk_mul_f32 v[14:15], v[14:15], v[16:17] op_sel_hi:[1,0]
	v_pk_mul_f32 v[8:9], v[8:9], v[16:17] op_sel_hi:[1,0]
	v_pk_mul_f32 v[10:11], v[10:11], v[16:17] op_sel_hi:[1,0]
	v_pk_mul_f32 v[4:5], v[4:5], v[16:17] op_sel_hi:[1,0]
	v_pk_mul_f32 v[6:7], v[6:7], v[16:17] op_sel_hi:[1,0]
	v_pk_mul_f32 v[0:1], v[0:1], v[16:17] op_sel_hi:[1,0]
	v_pk_mul_f32 v[2:3], v[2:3], v[16:17] op_sel_hi:[1,0]
	v_pk_mul_f32 v[14:15], v[166:167], v[14:15]
	v_pk_mul_f32 v[12:13], v[164:165], v[12:13]
	v_pk_mul_f32 v[10:11], v[162:163], v[10:11]
	v_pk_mul_f32 v[8:9], v[160:161], v[8:9]
	v_pk_mul_f32 v[6:7], v[158:159], v[6:7]
	v_pk_mul_f32 v[4:5], v[156:157], v[4:5]
	v_pk_mul_f32 v[2:3], v[154:155], v[2:3]
	v_pk_mul_f32 v[0:1], v[152:153], v[0:1]

.LBB0_357:
	s_or_b64 exec, exec, s[4:5]
	s_and_b64 vcc, exec, s[2:3]
	s_cbranch_vccz .Lp1_nonext
	s_lshl_b32 s4, s44, 8
	v_add_u32_e32 v248, s4, v141
	v_mov_b32_e32 v249, 0
	v_lshl_add_u64 v[248:249], v[248:249], 2, s[18:19]
	global_load_dword v240, v[248:249], off
	global_load_dword v241, v[248:249], off offset:64
	global_load_dword v242, v[248:249], off offset:128
	global_load_dword v243, v[248:249], off offset:192
	global_load_dword v244, v[248:249], off offset:512
	global_load_dword v245, v[248:249], off offset:576
	global_load_dword v246, v[248:249], off offset:640
	global_load_dword v247, v[248:249], off offset:704
.Lp1_nonext:
	s_andn2_b64 vcc, exec, s[2:3]
	s_mov_b64 s[2:3], -1
	s_cbranch_vccnz .LBB0_140
	s_andn2_b64 vcc, exec, s[16:17]
	s_cbranch_vccnz .LBB0_139
	s_barrier
	s_branch .LBB0_139
